# static wave priorities in phase 5: scan compute waves s_setprio 3 over their loader waves; attention waves 4-7 s_setprio 1
# speedup vs baseline: 1.0116x; 1.0067x over previous
; DI void scan_task(const Params& P, int sb, unsigned char* lds) {
;     ...
;   } else {
;     const int q = lane & 15, q4 = q * 4, rowl = w * 4 + (lane >> 4);
;     const bool o1 = (lane & 1) != 0, o2 = (lane & 2) != 0;
;     f2 S0 = {0.f, 0.f}, S1 = {0.f, 0.f};
;     __syncthreads();
;     ...
;   if ((int)gridDim.x == 2 * NSCAN) { if ((bx & 4) != 0) scan_task(P, (bx & 3) * 32 + (bx >> 3), lds); }
.LBB0_1193:
	s_andn2_b64 vcc, exec, s[4:5]
	s_cbranch_vccnz .LBB0_1235
	s_bitcmp0_b32 s76, 2
	s_cbranch_scc1 .LBB0_1235
	v_readfirstlane_b32 s1, v208
	s_cmpk_lt_u32 s1, 0x100
	s_mov_b64 s[4:5], -1
	s_waitcnt vmcnt(63) expcnt(7) lgkmcnt(15)
	s_barrier
	s_cbranch_scc0 .LBB0_1201
	s_setprio 3
	v_lshlrev_b32_e32 v0, 2, v208
	v_and_b32_e32 v68, 60, v0
	v_and_b32_e32 v0, 1, v208
	s_and_b32 s3, s1, 0xc0
	v_cmp_eq_u32_e32 vcc, 0, v0
	v_and_b32_e32 v0, 2, v208
	v_and_b32_e32 v1, 15, v208
	v_mov_b32_e32 v2, 0x1080
	v_cmp_eq_u32_e64 s[4:5], 0, v0
	v_bfe_u32 v0, v208, 2, 2
	v_lshl_add_u32 v69, v1, 4, v2
	v_and_or_b32 v1, v208, 48, s3
	v_lshrrev_b32_e32 v1, 2, v1
	v_lshlrev_b32_e32 v0, 6, v0
	s_mov_b32 s3, 0x16000
	v_or3_b32 v70, v1, v0, s3
	s_lshl_b32 s1, s1, 3
	v_lshlrev_b32_e32 v0, 3, v208
	v_mov_b32_e32 v64, 0
	s_and_b32 s1, s1, 0x600
	v_and_b32_e32 v0, 0x180, v0
	v_mov_b32_e32 v65, v64
	s_mov_b32 s0, 0
	v_or_b32_e32 v71, s1, v0
	s_mov_b64 s[6:7], 0
	s_mov_b32 s1, 0xb000
	v_mov_b64_e32 v[66:67], v[64:65]
	s_barrier

; template <int CTRL> DI float dppf(float v) { return __int_as_float(__builtin_amdgcn_update_dpp(0, __float_as_int(v), CTRL, 0xf, 0xf, false)); }
; DI float red16(float p) { p += dppf<0xB1>(p); p += dppf<0x4E>(p); p += dppf<0x141>(p); p += dppf<0x140>(p); return p; }
; DI void scan_task(const Params& P, int sb, unsigned char* lds) {
;     ...
;       for (int g4 = 0; g4 < CH / 4; ++g4) {
;         const float* gb = cb + g4 * 4 * SREC;
;         const float4 v4 = *(const float4*)(vrow + g4 * 4);
;         float pp[4];
; #pragma unroll
;         for (int i = 0; i < 4; ++i) {
;           ld_ops(nx3, gb + (i + 3) * SREC, q4);
;           const f2 a01 = {cur.a.x, cur.a.y}, a23 = {cur.a.z, cur.a.w}, w01 = {cur.w.x, cur.w.y}, w23 = {cur.w.z, cur.w.w};
;           const f2 k01 = {cur.k.x, cur.k.y}, k23 = {cur.k.z, cur.k.w}, b01 = {cur.b.x, cur.b.y}, b23 = {cur.b.z, cur.b.w};
;           const f2 r01 = {cur.r.x, cur.r.y}, r23 = {cur.r.z, cur.r.w};
;           f2 pa = S0 * a01; pa += S1 * a23;
;           const float vs = (i == 0) ? v4.x : (i == 1) ? v4.y : (i == 2) ? v4.z : v4.w;
;           const f2 vv = {vs, vs};
;           const f2 t0 = S0 * w01 + vv * k01, t1 = S1 * w23 + vv * k23;
;           const float sa = red16(pa.x + pa.y);
;           const f2 sa2 = {sa, sa};
;           S0 = t0 + sa2 * b01; S1 = t1 + sa2 * b23;
;           f2 py = S0 * r01; py += S1 * r23;
;           pp[i] = py.x + py.y;
;           cur = nxt; nxt = nx2; nx2 = nx3;
;         }
;         const float tA = o1 ? pp[0] : pp[1], kA = o1 ? pp[1] : pp[0];
;         const float tB = o1 ? pp[2] : pp[3], kB = o1 ? pp[3] : pp[2];
;         const float r0 = kA + dppf<0xB1>(tA), r1 = kB + dppf<0xB1>(tB);
;         const float tC = o2 ? r0 : r1, kC = o2 ? r1 : r0;
;         float u = kC + dppf<0x4E>(tC);
;         u += dppf<0x124>(u);
;         u += dppf<0x128>(u);
;         yb[(g4 * 4 + (q & 3)) * 16 + rowl] = u;
.LBB0_1198:
	s_waitcnt lgkmcnt(14)
	v_pk_mul_f32 v[2:3], v[64:65], v[2:3]
	ds_read_b128 v[60:63], v72 offset:256
	ds_read_b128 v[76:79], v72 offset:512
	ds_read_b128 v[80:83], v72 offset:768
	ds_read_b128 v[84:87], v72 offset:1024
	ds_read_b128 v[112:115], v100 offset:16
	ds_read_b128 v[92:95], v72
	v_pk_fma_f32 v[96:97], v[66:67], v[0:1], v[2:3]
	ds_read_b128 v[0:3], v72 offset:1408
	v_add_f32_e32 v75, v96, v97
	s_waitcnt lgkmcnt(7)
	v_pk_mul_f32 v[14:15], v[14:15], v[88:89] op_sel_hi:[1,0]
	v_pk_mul_f32 v[12:13], v[12:13], v[88:89] op_sel_hi:[1,0]
	v_add_f32_dpp v75, v75, v75 quad_perm:[1,0,3,2] row_mask:0xf bank_mask:0xf bound_ctrl:1
	v_pk_fma_f32 v[64:65], v[64:65], v[10:11], v[14:15]
	v_pk_fma_f32 v[66:67], v[66:67], v[8:9], v[12:13]
	v_add_f32_dpp v75, v75, v75 quad_perm:[2,3,0,1] row_mask:0xf bank_mask:0xf bound_ctrl:1
	v_mov_b32_e32 v98, v91
	ds_read_b128 v[8:11], v72 offset:1920
	ds_read_b128 v[12:15], v72 offset:2176
	v_add_f32_dpp v75, v75, v75 row_half_mirror row_mask:0xf bank_mask:0xf bound_ctrl:1
	s_nop 1
	v_add_f32_dpp v96, v75, v75 row_mirror row_mask:0xf bank_mask:0xf bound_ctrl:1
	v_pk_fma_f32 v[64:65], v[6:7], v[96:97], v[64:65] op_sel_hi:[1,0,1]
	v_pk_fma_f32 v[66:67], v[4:5], v[96:97], v[66:67] op_sel_hi:[1,0,1]
	v_pk_mul_f32 v[18:19], v[18:19], v[64:65]
	v_pk_mul_f32 v[22:23], v[22:23], v[64:65]
	v_pk_mul_f32 v[36:37], v[36:37], v[66:67]
	v_pk_mul_f32 v[38:39], v[38:39], v[64:65]
	v_pk_fma_f32 v[64:65], v[16:17], v[66:67], v[18:19]
	v_pk_fma_f32 v[66:67], v[20:21], v[66:67], v[22:23]
	v_add_f32_e32 v75, v64, v65
	v_add_f32_e32 v64, v66, v67
	v_pk_fma_f32 v[36:37], v[28:29], v[88:89], v[36:37] op_sel:[0,1,0]
	v_pk_fma_f32 v[38:39], v[30:31], v[88:89], v[38:39] op_sel:[0,1,0]
	v_add_f32_dpp v64, v64, v64 quad_perm:[1,0,3,2] row_mask:0xf bank_mask:0xf bound_ctrl:1
	ds_read_b128 v[4:7], v72 offset:1664
	ds_read_b128 v[16:19], v72 offset:2432
	v_add_f32_dpp v64, v64, v64 quad_perm:[2,3,0,1] row_mask:0xf bank_mask:0xf bound_ctrl:1
	ds_read_b128 v[20:23], v72 offset:2816
	ds_read_b128 v[28:31], v72 offset:3584
	v_add_f32_dpp v64, v64, v64 row_half_mirror row_mask:0xf bank_mask:0xf bound_ctrl:1
	s_nop 1
	v_add_f32_dpp v64, v64, v64 row_mirror row_mask:0xf bank_mask:0xf bound_ctrl:1
	v_pk_fma_f32 v[66:67], v[24:25], v[64:65], v[36:37] op_sel_hi:[1,0,1]
	v_pk_fma_f32 v[64:65], v[26:27], v[64:65], v[38:39] op_sel_hi:[1,0,1]
	v_pk_mul_f32 v[88:89], v[48:49], v[66:67]
	v_pk_mul_f32 v[34:35], v[34:35], v[64:65]
	v_pk_mul_f32 v[42:43], v[42:43], v[64:65]
	v_pk_fma_f32 v[96:97], v[32:33], v[66:67], v[34:35]
	v_pk_fma_f32 v[66:67], v[40:41], v[66:67], v[42:43]
	v_pk_mul_f32 v[64:65], v[50:51], v[64:65]
	v_add_f32_e32 v66, v66, v67
	v_pk_fma_f32 v[88:89], v[52:53], v[90:91], v[88:89] op_sel_hi:[1,0,1]
	v_pk_fma_f32 v[64:65], v[54:55], v[90:91], v[64:65] op_sel_hi:[1,0,1]
	v_add_f32_dpp v66, v66, v66 quad_perm:[1,0,3,2] row_mask:0xf bank_mask:0xf bound_ctrl:1
	v_add_f32_e32 v90, v96, v97
	v_add_f32_dpp v105, v75, v75 row_ror:8 row_mask:0xf bank_mask:0x3 bound_ctrl:1
	v_add_f32_dpp v66, v66, v66 quad_perm:[2,3,0,1] row_mask:0xf bank_mask:0xf bound_ctrl:1
	v_add_f32_dpp v107, v90, v90 row_ror:8 row_mask:0xf bank_mask:0x3 bound_ctrl:1
	ds_read_b128 v[24:27], v72 offset:3072
	ds_read_b128 v[36:39], v72 offset:3328
	v_add_f32_dpp v66, v66, v66 row_half_mirror row_mask:0xf bank_mask:0xf bound_ctrl:1
	ds_read_b128 v[48:51], v72 offset:4736
	ds_read_b128 v[32:35], v72 offset:3840
	v_add_f32_dpp v66, v66, v66 row_mirror row_mask:0xf bank_mask:0xf bound_ctrl:1
	v_pk_fma_f32 v[64:65], v[46:47], v[66:67], v[64:65] op_sel_hi:[1,0,1]
	v_pk_fma_f32 v[88:89], v[44:45], v[66:67], v[88:89] op_sel_hi:[1,0,1]
	s_waitcnt lgkmcnt(11)
	v_pk_mul_f32 v[66:67], v[94:95], v[64:65]
	v_pk_mul_f32 v[58:59], v[58:59], v[64:65]
	v_pk_fma_f32 v[66:67], v[92:93], v[88:89], v[66:67]
	v_pk_mul_f32 v[64:65], v[78:79], v[64:65]
	v_add_f32_e32 v66, v66, v67
	v_pk_fma_f32 v[78:79], v[56:57], v[88:89], v[58:59]
	v_pk_mul_f32 v[76:77], v[76:77], v[88:89]
	v_add_f32_dpp v66, v66, v66 quad_perm:[1,0,3,2] row_mask:0xf bank_mask:0xf bound_ctrl:1
	v_pk_fma_f32 v[64:65], v[98:99], v[82:83], v[64:65] op_sel_hi:[0,1,1]
	v_add_f32_e32 v104, v78, v79
	v_add_f32_dpp v66, v66, v66 quad_perm:[2,3,0,1] row_mask:0xf bank_mask:0xf bound_ctrl:1
	v_pk_fma_f32 v[76:77], v[98:99], v[80:81], v[76:77] op_sel_hi:[0,1,1]
	ds_read_b128 v[40:43], v72 offset:4224
	ds_read_b128 v[52:55], v72 offset:4992
	v_add_f32_dpp v66, v66, v66 row_half_mirror row_mask:0xf bank_mask:0xf bound_ctrl:1
	ds_read_b128 v[44:47], v72 offset:4480
	ds_read_b128 v[56:59], v72 offset:5248
	v_add_f32_dpp v78, v66, v66 row_mirror row_mask:0xf bank_mask:0xf bound_ctrl:1
	v_pk_fma_f32 v[64:65], v[62:63], v[78:79], v[64:65] op_sel_hi:[1,0,1]
	v_pk_fma_f32 v[66:67], v[60:61], v[78:79], v[76:77] op_sel_hi:[1,0,1]
	v_pk_mul_f32 v[102:103], v[86:87], v[64:65]
	v_pk_fma_f32 v[102:103], v[84:85], v[66:67], v[102:103]
	s_waitcnt lgkmcnt(14)
	v_pk_mul_f32 v[2:3], v[64:65], v[2:3]
	v_add_f32_e32 v102, v102, v103
	ds_read_b128 v[60:63], v72 offset:5888
	v_add_f32_dpp v105, v104, v104 row_ror:8 row_mask:0xf bank_mask:0xc bound_ctrl:1
	ds_read_b128 v[76:79], v72 offset:6144
	ds_read_b128 v[80:83], v72 offset:6400
	ds_read_b128 v[84:87], v72 offset:6656
	ds_read_b128 v[88:91], v100 offset:32
	ds_read_b128 v[92:95], v72 offset:5632
	v_add_f32_dpp v107, v102, v102 row_ror:8 row_mask:0xf bank_mask:0xc bound_ctrl:1
	v_pk_fma_f32 v[96:97], v[66:67], v[0:1], v[2:3]
	v_add_f32_dpp v108, v105, v105 row_half_mirror row_mask:0xf bank_mask:0x5 bound_ctrl:1
	v_add_f32_dpp v108, v107, v107 row_half_mirror row_mask:0xf bank_mask:0xa bound_ctrl:1
	ds_read_b128 v[0:3], v72 offset:7040
	v_add_f32_e32 v75, v96, v97
	s_waitcnt lgkmcnt(7)
; template <int CTRL> DI float dppf(float v) { return __int_as_float(__builtin_amdgcn_update_dpp(0, __float_as_int(v), CTRL, 0xf, 0xf, false)); }
; DI float red16(float p) { p += dppf<0xB1>(p); p += dppf<0x4E>(p); p += dppf<0x141>(p); p += dppf<0x140>(p); return p; }
; DI void scan_task(const Params& P, int sb, unsigned char* lds) {
;     ...
;       for (int g4 = 0; g4 < CH / 4; ++g4) {
;         const float* gb = cb + g4 * 4 * SREC;
;         const float4 v4 = *(const float4*)(vrow + g4 * 4);
;         float pp[4];
; #pragma unroll
;         for (int i = 0; i < 4; ++i) {
;           ld_ops(nx3, gb + (i + 3) * SREC, q4);
;           const f2 a01 = {cur.a.x, cur.a.y}, a23 = {cur.a.z, cur.a.w}, w01 = {cur.w.x, cur.w.y}, w23 = {cur.w.z, cur.w.w};
;           const f2 k01 = {cur.k.x, cur.k.y}, k23 = {cur.k.z, cur.k.w}, b01 = {cur.b.x, cur.b.y}, b23 = {cur.b.z, cur.b.w};
;           const f2 r01 = {cur.r.x, cur.r.y}, r23 = {cur.r.z, cur.r.w};
;           f2 pa = S0 * a01; pa += S1 * a23;
;           const float vs = (i == 0) ? v4.x : (i == 1) ? v4.y : (i == 2) ? v4.z : v4.w;
;           const f2 vv = {vs, vs};
;           const f2 t0 = S0 * w01 + vv * k01, t1 = S1 * w23 + vv * k23;
;           const float sa = red16(pa.x + pa.y);
;           const f2 sa2 = {sa, sa};
;           S0 = t0 + sa2 * b01; S1 = t1 + sa2 * b23;
;           f2 py = S0 * r01; py += S1 * r23;
;           pp[i] = py.x + py.y;
;           cur = nxt; nxt = nx2; nx2 = nx3;
;         }
;         const float tA = o1 ? pp[0] : pp[1], kA = o1 ? pp[1] : pp[0];
;         const float tB = o1 ? pp[2] : pp[3], kB = o1 ? pp[3] : pp[2];
;         const float r0 = kA + dppf<0xB1>(tA), r1 = kB + dppf<0xB1>(tB);
;         const float tC = o2 ? r0 : r1, kC = o2 ? r1 : r0;
;         float u = kC + dppf<0x4E>(tC);
;         u += dppf<0x124>(u);
;         u += dppf<0x128>(u);
;         yb[(g4 * 4 + (q & 3)) * 16 + rowl] = u;
	v_add_f32_dpp v108, v108, v108 quad_perm:[1,0,3,2] row_mask:0xf bank_mask:0xf bound_ctrl:1
	v_pk_mul_f32 v[14:15], v[14:15], v[112:113] op_sel_hi:[1,0]
	v_pk_mul_f32 v[12:13], v[12:13], v[112:113] op_sel_hi:[1,0]
	v_add_f32_dpp v108, v108, v108 quad_perm:[2,3,0,1] row_mask:0xf bank_mask:0xf bound_ctrl:1
	v_add_f32_dpp v75, v75, v75 quad_perm:[1,0,3,2] row_mask:0xf bank_mask:0xf bound_ctrl:1
	v_pk_fma_f32 v[64:65], v[64:65], v[10:11], v[14:15]
	v_pk_fma_f32 v[66:67], v[66:67], v[8:9], v[12:13]
	v_add_f32_dpp v75, v75, v75 quad_perm:[2,3,0,1] row_mask:0xf bank_mask:0xf bound_ctrl:1
	v_mov_b32_e32 v98, v115
	ds_write_b32 v73, v108
	v_add_f32_dpp v75, v75, v75 row_half_mirror row_mask:0xf bank_mask:0xf bound_ctrl:1
	ds_read_b128 v[8:11], v72 offset:7552
	ds_read_b128 v[12:15], v72 offset:7808
	v_add_f32_dpp v96, v75, v75 row_mirror row_mask:0xf bank_mask:0xf bound_ctrl:1
	v_pk_fma_f32 v[64:65], v[6:7], v[96:97], v[64:65] op_sel_hi:[1,0,1]
	v_pk_fma_f32 v[66:67], v[4:5], v[96:97], v[66:67] op_sel_hi:[1,0,1]
	v_pk_mul_f32 v[18:19], v[18:19], v[64:65]
	v_pk_mul_f32 v[22:23], v[22:23], v[64:65]
	v_pk_mul_f32 v[36:37], v[36:37], v[66:67]
	v_pk_mul_f32 v[38:39], v[38:39], v[64:65]
	v_pk_fma_f32 v[64:65], v[16:17], v[66:67], v[18:19]
	v_pk_fma_f32 v[66:67], v[20:21], v[66:67], v[22:23]
	v_add_f32_e32 v75, v64, v65
	v_add_f32_e32 v64, v66, v67
	v_pk_fma_f32 v[36:37], v[28:29], v[112:113], v[36:37] op_sel:[0,1,0]
	v_pk_fma_f32 v[38:39], v[30:31], v[112:113], v[38:39] op_sel:[0,1,0]
	v_add_f32_dpp v64, v64, v64 quad_perm:[1,0,3,2] row_mask:0xf bank_mask:0xf bound_ctrl:1
	ds_read_b128 v[4:7], v72 offset:7296
	ds_read_b128 v[16:19], v72 offset:8064
	v_add_f32_dpp v64, v64, v64 quad_perm:[2,3,0,1] row_mask:0xf bank_mask:0xf bound_ctrl:1
	ds_read_b128 v[20:23], v72 offset:8448
	ds_read_b128 v[28:31], v72 offset:9216
	v_add_f32_dpp v64, v64, v64 row_half_mirror row_mask:0xf bank_mask:0xf bound_ctrl:1
	s_nop 1
	v_add_f32_dpp v64, v64, v64 row_mirror row_mask:0xf bank_mask:0xf bound_ctrl:1
	v_pk_fma_f32 v[66:67], v[24:25], v[64:65], v[36:37] op_sel_hi:[1,0,1]
	v_pk_fma_f32 v[64:65], v[26:27], v[64:65], v[38:39] op_sel_hi:[1,0,1]
	v_pk_mul_f32 v[112:113], v[48:49], v[66:67]
	v_pk_mul_f32 v[34:35], v[34:35], v[64:65]
	v_pk_mul_f32 v[42:43], v[42:43], v[64:65]
	v_pk_fma_f32 v[96:97], v[32:33], v[66:67], v[34:35]
	v_pk_fma_f32 v[66:67], v[40:41], v[66:67], v[42:43]
	v_pk_mul_f32 v[64:65], v[50:51], v[64:65]
	v_add_f32_e32 v66, v66, v67
	v_pk_fma_f32 v[112:113], v[52:53], v[114:115], v[112:113] op_sel_hi:[1,0,1]
	v_pk_fma_f32 v[64:65], v[54:55], v[114:115], v[64:65] op_sel_hi:[1,0,1]
	v_add_f32_dpp v66, v66, v66 quad_perm:[1,0,3,2] row_mask:0xf bank_mask:0xf bound_ctrl:1
	v_add_f32_e32 v114, v96, v97
	v_add_f32_dpp v105, v75, v75 row_ror:8 row_mask:0xf bank_mask:0x3 bound_ctrl:1
	v_add_f32_dpp v66, v66, v66 quad_perm:[2,3,0,1] row_mask:0xf bank_mask:0xf bound_ctrl:1
	v_add_f32_dpp v107, v114, v114 row_ror:8 row_mask:0xf bank_mask:0x3 bound_ctrl:1
	ds_read_b128 v[24:27], v72 offset:8704
	ds_read_b128 v[36:39], v72 offset:8960
	v_add_f32_dpp v66, v66, v66 row_half_mirror row_mask:0xf bank_mask:0xf bound_ctrl:1
	ds_read_b128 v[48:51], v72 offset:10368
	ds_read_b128 v[32:35], v72 offset:9472
	v_add_f32_dpp v66, v66, v66 row_mirror row_mask:0xf bank_mask:0xf bound_ctrl:1
	v_pk_fma_f32 v[64:65], v[46:47], v[66:67], v[64:65] op_sel_hi:[1,0,1]
	v_pk_fma_f32 v[112:113], v[44:45], v[66:67], v[112:113] op_sel_hi:[1,0,1]
	s_waitcnt lgkmcnt(11)
	v_pk_mul_f32 v[66:67], v[94:95], v[64:65]
	v_pk_mul_f32 v[58:59], v[58:59], v[64:65]
	v_pk_fma_f32 v[66:67], v[92:93], v[112:113], v[66:67]
	v_pk_mul_f32 v[64:65], v[78:79], v[64:65]
	v_add_f32_e32 v66, v66, v67
	v_pk_fma_f32 v[78:79], v[56:57], v[112:113], v[58:59]
	v_pk_mul_f32 v[76:77], v[76:77], v[112:113]
	v_add_f32_dpp v66, v66, v66 quad_perm:[1,0,3,2] row_mask:0xf bank_mask:0xf bound_ctrl:1
	v_pk_fma_f32 v[64:65], v[98:99], v[82:83], v[64:65] op_sel_hi:[0,1,1]
	v_add_f32_e32 v104, v78, v79
	v_add_f32_dpp v66, v66, v66 quad_perm:[2,3,0,1] row_mask:0xf bank_mask:0xf bound_ctrl:1
	v_pk_fma_f32 v[76:77], v[98:99], v[80:81], v[76:77] op_sel_hi:[0,1,1]
	ds_read_b128 v[40:43], v72 offset:9856
	ds_read_b128 v[52:55], v72 offset:10624
	v_add_f32_dpp v66, v66, v66 row_half_mirror row_mask:0xf bank_mask:0xf bound_ctrl:1
	ds_read_b128 v[44:47], v72 offset:10112
	ds_read_b128 v[56:59], v72 offset:10880
	v_add_f32_dpp v78, v66, v66 row_mirror row_mask:0xf bank_mask:0xf bound_ctrl:1
	v_pk_fma_f32 v[64:65], v[62:63], v[78:79], v[64:65] op_sel_hi:[1,0,1]
	v_pk_fma_f32 v[66:67], v[60:61], v[78:79], v[76:77] op_sel_hi:[1,0,1]
	v_pk_mul_f32 v[102:103], v[86:87], v[64:65]
	v_pk_fma_f32 v[102:103], v[84:85], v[66:67], v[102:103]
	s_waitcnt lgkmcnt(14)
	v_pk_mul_f32 v[2:3], v[64:65], v[2:3]
	v_add_f32_e32 v102, v102, v103
	ds_read_b128 v[60:63], v72 offset:11520
	v_add_f32_dpp v105, v104, v104 row_ror:8 row_mask:0xf bank_mask:0xc bound_ctrl:1
	ds_read_b128 v[76:79], v72 offset:11776
	ds_read_b128 v[80:83], v72 offset:12032
	ds_read_b128 v[84:87], v72 offset:12288
	ds_read_b128 v[112:115], v100 offset:48
	ds_read_b128 v[92:95], v72 offset:11264
	v_add_f32_dpp v107, v102, v102 row_ror:8 row_mask:0xf bank_mask:0xc bound_ctrl:1
	v_pk_fma_f32 v[96:97], v[66:67], v[0:1], v[2:3]
	v_add_f32_dpp v108, v105, v105 row_half_mirror row_mask:0xf bank_mask:0x5 bound_ctrl:1
	v_add_f32_dpp v108, v107, v107 row_half_mirror row_mask:0xf bank_mask:0xa bound_ctrl:1
	ds_read_b128 v[0:3], v72 offset:12672
	v_add_f32_e32 v75, v96, v97
	s_waitcnt lgkmcnt(7)
; template <int CTRL> DI float dppf(float v) { return __int_as_float(__builtin_amdgcn_update_dpp(0, __float_as_int(v), CTRL, 0xf, 0xf, false)); }
; DI float red16(float p) { p += dppf<0xB1>(p); p += dppf<0x4E>(p); p += dppf<0x141>(p); p += dppf<0x140>(p); return p; }
; DI void scan_task(const Params& P, int sb, unsigned char* lds) {
;     ...
;       for (int g4 = 0; g4 < CH / 4; ++g4) {
;         const float* gb = cb + g4 * 4 * SREC;
;         const float4 v4 = *(const float4*)(vrow + g4 * 4);
;         float pp[4];
; #pragma unroll
;         for (int i = 0; i < 4; ++i) {
;           ld_ops(nx3, gb + (i + 3) * SREC, q4);
;           const f2 a01 = {cur.a.x, cur.a.y}, a23 = {cur.a.z, cur.a.w}, w01 = {cur.w.x, cur.w.y}, w23 = {cur.w.z, cur.w.w};
;           const f2 k01 = {cur.k.x, cur.k.y}, k23 = {cur.k.z, cur.k.w}, b01 = {cur.b.x, cur.b.y}, b23 = {cur.b.z, cur.b.w};
;           const f2 r01 = {cur.r.x, cur.r.y}, r23 = {cur.r.z, cur.r.w};
;           f2 pa = S0 * a01; pa += S1 * a23;
;           const float vs = (i == 0) ? v4.x : (i == 1) ? v4.y : (i == 2) ? v4.z : v4.w;
;           const f2 vv = {vs, vs};
;           const f2 t0 = S0 * w01 + vv * k01, t1 = S1 * w23 + vv * k23;
;           const float sa = red16(pa.x + pa.y);
;           const f2 sa2 = {sa, sa};
;           S0 = t0 + sa2 * b01; S1 = t1 + sa2 * b23;
;           f2 py = S0 * r01; py += S1 * r23;
;           pp[i] = py.x + py.y;
;           cur = nxt; nxt = nx2; nx2 = nx3;
;         }
;         const float tA = o1 ? pp[0] : pp[1], kA = o1 ? pp[1] : pp[0];
;         const float tB = o1 ? pp[2] : pp[3], kB = o1 ? pp[3] : pp[2];
;         const float r0 = kA + dppf<0xB1>(tA), r1 = kB + dppf<0xB1>(tB);
;         const float tC = o2 ? r0 : r1, kC = o2 ? r1 : r0;
;         float u = kC + dppf<0x4E>(tC);
;         u += dppf<0x124>(u);
;         u += dppf<0x128>(u);
;         yb[(g4 * 4 + (q & 3)) * 16 + rowl] = u;
	v_add_f32_dpp v108, v108, v108 quad_perm:[1,0,3,2] row_mask:0xf bank_mask:0xf bound_ctrl:1
	v_pk_mul_f32 v[14:15], v[14:15], v[88:89] op_sel_hi:[1,0]
	v_pk_mul_f32 v[12:13], v[12:13], v[88:89] op_sel_hi:[1,0]
	v_add_f32_dpp v108, v108, v108 quad_perm:[2,3,0,1] row_mask:0xf bank_mask:0xf bound_ctrl:1
	v_add_f32_dpp v75, v75, v75 quad_perm:[1,0,3,2] row_mask:0xf bank_mask:0xf bound_ctrl:1
	v_pk_fma_f32 v[64:65], v[64:65], v[10:11], v[14:15]
	v_pk_fma_f32 v[66:67], v[66:67], v[8:9], v[12:13]
	v_add_f32_dpp v75, v75, v75 quad_perm:[2,3,0,1] row_mask:0xf bank_mask:0xf bound_ctrl:1
	v_mov_b32_e32 v98, v91
	ds_write_b32 v73, v108 offset:256
	v_add_f32_dpp v75, v75, v75 row_half_mirror row_mask:0xf bank_mask:0xf bound_ctrl:1
	ds_read_b128 v[8:11], v72 offset:13184
	ds_read_b128 v[12:15], v72 offset:13440
	v_add_f32_dpp v96, v75, v75 row_mirror row_mask:0xf bank_mask:0xf bound_ctrl:1
	v_pk_fma_f32 v[64:65], v[6:7], v[96:97], v[64:65] op_sel_hi:[1,0,1]
	v_pk_fma_f32 v[66:67], v[4:5], v[96:97], v[66:67] op_sel_hi:[1,0,1]
	v_pk_mul_f32 v[18:19], v[18:19], v[64:65]
	v_pk_mul_f32 v[22:23], v[22:23], v[64:65]
	v_pk_mul_f32 v[36:37], v[36:37], v[66:67]
	v_pk_mul_f32 v[38:39], v[38:39], v[64:65]
	v_pk_fma_f32 v[64:65], v[16:17], v[66:67], v[18:19]
	v_pk_fma_f32 v[66:67], v[20:21], v[66:67], v[22:23]
	v_add_f32_e32 v75, v64, v65
	v_add_f32_e32 v64, v66, v67
	v_pk_fma_f32 v[36:37], v[28:29], v[88:89], v[36:37] op_sel:[0,1,0]
	v_pk_fma_f32 v[38:39], v[30:31], v[88:89], v[38:39] op_sel:[0,1,0]
	v_add_f32_dpp v64, v64, v64 quad_perm:[1,0,3,2] row_mask:0xf bank_mask:0xf bound_ctrl:1
	ds_read_b128 v[4:7], v72 offset:12928
	ds_read_b128 v[16:19], v72 offset:13696
	v_add_f32_dpp v64, v64, v64 quad_perm:[2,3,0,1] row_mask:0xf bank_mask:0xf bound_ctrl:1
	ds_read_b128 v[20:23], v72 offset:14080
	ds_read_b128 v[28:31], v72 offset:14848
	v_add_f32_dpp v64, v64, v64 row_half_mirror row_mask:0xf bank_mask:0xf bound_ctrl:1
	s_nop 1
	v_add_f32_dpp v64, v64, v64 row_mirror row_mask:0xf bank_mask:0xf bound_ctrl:1
	v_pk_fma_f32 v[66:67], v[24:25], v[64:65], v[36:37] op_sel_hi:[1,0,1]
	v_pk_fma_f32 v[64:65], v[26:27], v[64:65], v[38:39] op_sel_hi:[1,0,1]
	v_pk_mul_f32 v[88:89], v[48:49], v[66:67]
	v_pk_mul_f32 v[34:35], v[34:35], v[64:65]
	v_pk_mul_f32 v[42:43], v[42:43], v[64:65]
	v_pk_fma_f32 v[96:97], v[32:33], v[66:67], v[34:35]
	v_pk_fma_f32 v[66:67], v[40:41], v[66:67], v[42:43]
	v_pk_mul_f32 v[64:65], v[50:51], v[64:65]
	v_add_f32_e32 v66, v66, v67
	v_pk_fma_f32 v[88:89], v[52:53], v[90:91], v[88:89] op_sel_hi:[1,0,1]
	v_pk_fma_f32 v[64:65], v[54:55], v[90:91], v[64:65] op_sel_hi:[1,0,1]
	v_add_f32_dpp v66, v66, v66 quad_perm:[1,0,3,2] row_mask:0xf bank_mask:0xf bound_ctrl:1
	v_add_f32_e32 v90, v96, v97
	v_add_f32_dpp v105, v75, v75 row_ror:8 row_mask:0xf bank_mask:0x3 bound_ctrl:1
	v_add_f32_dpp v66, v66, v66 quad_perm:[2,3,0,1] row_mask:0xf bank_mask:0xf bound_ctrl:1
	v_add_f32_dpp v107, v90, v90 row_ror:8 row_mask:0xf bank_mask:0x3 bound_ctrl:1
	ds_read_b128 v[24:27], v72 offset:14336
	ds_read_b128 v[36:39], v72 offset:14592
	v_add_f32_dpp v66, v66, v66 row_half_mirror row_mask:0xf bank_mask:0xf bound_ctrl:1
	ds_read_b128 v[48:51], v72 offset:16000
	ds_read_b128 v[32:35], v72 offset:15104
	v_add_f32_dpp v66, v66, v66 row_mirror row_mask:0xf bank_mask:0xf bound_ctrl:1
	v_pk_fma_f32 v[64:65], v[46:47], v[66:67], v[64:65] op_sel_hi:[1,0,1]
	v_pk_fma_f32 v[88:89], v[44:45], v[66:67], v[88:89] op_sel_hi:[1,0,1]
	s_waitcnt lgkmcnt(11)
	v_pk_mul_f32 v[66:67], v[94:95], v[64:65]
	v_pk_mul_f32 v[58:59], v[58:59], v[64:65]
	v_pk_fma_f32 v[66:67], v[92:93], v[88:89], v[66:67]
	v_pk_mul_f32 v[64:65], v[78:79], v[64:65]
	v_add_f32_e32 v66, v66, v67
	v_pk_fma_f32 v[78:79], v[56:57], v[88:89], v[58:59]
	v_pk_mul_f32 v[76:77], v[76:77], v[88:89]
	v_add_f32_dpp v66, v66, v66 quad_perm:[1,0,3,2] row_mask:0xf bank_mask:0xf bound_ctrl:1
	v_pk_fma_f32 v[64:65], v[98:99], v[82:83], v[64:65] op_sel_hi:[0,1,1]
	v_add_f32_e32 v104, v78, v79
	v_add_f32_dpp v66, v66, v66 quad_perm:[2,3,0,1] row_mask:0xf bank_mask:0xf bound_ctrl:1
	v_pk_fma_f32 v[76:77], v[98:99], v[80:81], v[76:77] op_sel_hi:[0,1,1]
	ds_read_b128 v[40:43], v72 offset:15488
	ds_read_b128 v[52:55], v72 offset:16256
	v_add_f32_dpp v66, v66, v66 row_half_mirror row_mask:0xf bank_mask:0xf bound_ctrl:1
	ds_read_b128 v[44:47], v72 offset:15744
	ds_read_b128 v[56:59], v72 offset:16512
	v_add_f32_dpp v78, v66, v66 row_mirror row_mask:0xf bank_mask:0xf bound_ctrl:1
	v_pk_fma_f32 v[64:65], v[62:63], v[78:79], v[64:65] op_sel_hi:[1,0,1]
	v_pk_fma_f32 v[66:67], v[60:61], v[78:79], v[76:77] op_sel_hi:[1,0,1]
	v_pk_mul_f32 v[102:103], v[86:87], v[64:65]
	v_pk_fma_f32 v[102:103], v[84:85], v[66:67], v[102:103]
	s_waitcnt lgkmcnt(14)
	v_pk_mul_f32 v[2:3], v[64:65], v[2:3]
	v_add_f32_e32 v102, v102, v103
	ds_read_b128 v[60:63], v72 offset:17152
	v_add_f32_dpp v105, v104, v104 row_ror:8 row_mask:0xf bank_mask:0xc bound_ctrl:1
	ds_read_b128 v[76:79], v72 offset:17408
	ds_read_b128 v[80:83], v72 offset:17664
	ds_read_b128 v[84:87], v72 offset:17920
	ds_read_b128 v[88:91], v100 offset:64
	ds_read_b128 v[92:95], v72 offset:16896
	v_add_f32_dpp v107, v102, v102 row_ror:8 row_mask:0xf bank_mask:0xc bound_ctrl:1
	v_pk_fma_f32 v[96:97], v[66:67], v[0:1], v[2:3]
	v_add_f32_dpp v108, v105, v105 row_half_mirror row_mask:0xf bank_mask:0x5 bound_ctrl:1
	v_add_f32_dpp v108, v107, v107 row_half_mirror row_mask:0xf bank_mask:0xa bound_ctrl:1
	ds_read_b128 v[0:3], v72 offset:18304
	v_add_f32_e32 v75, v96, v97
	s_waitcnt lgkmcnt(7)
; template <int CTRL> DI float dppf(float v) { return __int_as_float(__builtin_amdgcn_update_dpp(0, __float_as_int(v), CTRL, 0xf, 0xf, false)); }
; DI float red16(float p) { p += dppf<0xB1>(p); p += dppf<0x4E>(p); p += dppf<0x141>(p); p += dppf<0x140>(p); return p; }
; DI void scan_task(const Params& P, int sb, unsigned char* lds) {
;     ...
;       for (int g4 = 0; g4 < CH / 4; ++g4) {
;         const float* gb = cb + g4 * 4 * SREC;
;         const float4 v4 = *(const float4*)(vrow + g4 * 4);
;         float pp[4];
; #pragma unroll
;         for (int i = 0; i < 4; ++i) {
;           ld_ops(nx3, gb + (i + 3) * SREC, q4);
;           const f2 a01 = {cur.a.x, cur.a.y}, a23 = {cur.a.z, cur.a.w}, w01 = {cur.w.x, cur.w.y}, w23 = {cur.w.z, cur.w.w};
;           const f2 k01 = {cur.k.x, cur.k.y}, k23 = {cur.k.z, cur.k.w}, b01 = {cur.b.x, cur.b.y}, b23 = {cur.b.z, cur.b.w};
;           const f2 r01 = {cur.r.x, cur.r.y}, r23 = {cur.r.z, cur.r.w};
;           f2 pa = S0 * a01; pa += S1 * a23;
;           const float vs = (i == 0) ? v4.x : (i == 1) ? v4.y : (i == 2) ? v4.z : v4.w;
;           const f2 vv = {vs, vs};
;           const f2 t0 = S0 * w01 + vv * k01, t1 = S1 * w23 + vv * k23;
;           const float sa = red16(pa.x + pa.y);
;           const f2 sa2 = {sa, sa};
;           S0 = t0 + sa2 * b01; S1 = t1 + sa2 * b23;
;           f2 py = S0 * r01; py += S1 * r23;
;           pp[i] = py.x + py.y;
;           cur = nxt; nxt = nx2; nx2 = nx3;
;         }
;         const float tA = o1 ? pp[0] : pp[1], kA = o1 ? pp[1] : pp[0];
;         const float tB = o1 ? pp[2] : pp[3], kB = o1 ? pp[3] : pp[2];
;         const float r0 = kA + dppf<0xB1>(tA), r1 = kB + dppf<0xB1>(tB);
;         const float tC = o2 ? r0 : r1, kC = o2 ? r1 : r0;
;         float u = kC + dppf<0x4E>(tC);
;         u += dppf<0x124>(u);
;         u += dppf<0x128>(u);
;         yb[(g4 * 4 + (q & 3)) * 16 + rowl] = u;
	v_add_f32_dpp v108, v108, v108 quad_perm:[1,0,3,2] row_mask:0xf bank_mask:0xf bound_ctrl:1
	v_pk_mul_f32 v[14:15], v[14:15], v[112:113] op_sel_hi:[1,0]
	v_pk_mul_f32 v[12:13], v[12:13], v[112:113] op_sel_hi:[1,0]
	v_add_f32_dpp v108, v108, v108 quad_perm:[2,3,0,1] row_mask:0xf bank_mask:0xf bound_ctrl:1
	v_add_f32_dpp v75, v75, v75 quad_perm:[1,0,3,2] row_mask:0xf bank_mask:0xf bound_ctrl:1
	v_pk_fma_f32 v[64:65], v[64:65], v[10:11], v[14:15]
	v_pk_fma_f32 v[66:67], v[66:67], v[8:9], v[12:13]
	v_add_f32_dpp v75, v75, v75 quad_perm:[2,3,0,1] row_mask:0xf bank_mask:0xf bound_ctrl:1
	v_mov_b32_e32 v98, v115
	ds_write_b32 v73, v108 offset:512
	v_add_f32_dpp v75, v75, v75 row_half_mirror row_mask:0xf bank_mask:0xf bound_ctrl:1
	ds_read_b128 v[8:11], v72 offset:18816
	ds_read_b128 v[12:15], v72 offset:19072
	v_add_f32_dpp v96, v75, v75 row_mirror row_mask:0xf bank_mask:0xf bound_ctrl:1
	v_pk_fma_f32 v[64:65], v[6:7], v[96:97], v[64:65] op_sel_hi:[1,0,1]
	v_pk_fma_f32 v[66:67], v[4:5], v[96:97], v[66:67] op_sel_hi:[1,0,1]
	v_pk_mul_f32 v[18:19], v[18:19], v[64:65]
	v_pk_mul_f32 v[22:23], v[22:23], v[64:65]
	v_pk_mul_f32 v[36:37], v[36:37], v[66:67]
	v_pk_mul_f32 v[38:39], v[38:39], v[64:65]
	v_pk_fma_f32 v[64:65], v[16:17], v[66:67], v[18:19]
	v_pk_fma_f32 v[66:67], v[20:21], v[66:67], v[22:23]
	v_add_f32_e32 v75, v64, v65
	v_add_f32_e32 v64, v66, v67
	v_pk_fma_f32 v[36:37], v[28:29], v[112:113], v[36:37] op_sel:[0,1,0]
	v_pk_fma_f32 v[38:39], v[30:31], v[112:113], v[38:39] op_sel:[0,1,0]
	v_add_f32_dpp v64, v64, v64 quad_perm:[1,0,3,2] row_mask:0xf bank_mask:0xf bound_ctrl:1
	ds_read_b128 v[4:7], v72 offset:18560
	ds_read_b128 v[16:19], v72 offset:19328
	v_add_f32_dpp v64, v64, v64 quad_perm:[2,3,0,1] row_mask:0xf bank_mask:0xf bound_ctrl:1
	ds_read_b128 v[20:23], v72 offset:19712
	ds_read_b128 v[28:31], v72 offset:20480
	v_add_f32_dpp v64, v64, v64 row_half_mirror row_mask:0xf bank_mask:0xf bound_ctrl:1
	s_nop 1
	v_add_f32_dpp v64, v64, v64 row_mirror row_mask:0xf bank_mask:0xf bound_ctrl:1
	v_pk_fma_f32 v[66:67], v[24:25], v[64:65], v[36:37] op_sel_hi:[1,0,1]
	v_pk_fma_f32 v[64:65], v[26:27], v[64:65], v[38:39] op_sel_hi:[1,0,1]
	v_pk_mul_f32 v[112:113], v[48:49], v[66:67]
	v_pk_mul_f32 v[34:35], v[34:35], v[64:65]
	v_pk_mul_f32 v[42:43], v[42:43], v[64:65]
	v_pk_fma_f32 v[96:97], v[32:33], v[66:67], v[34:35]
	v_pk_fma_f32 v[66:67], v[40:41], v[66:67], v[42:43]
	v_pk_mul_f32 v[64:65], v[50:51], v[64:65]
	v_add_f32_e32 v66, v66, v67
	v_pk_fma_f32 v[112:113], v[52:53], v[114:115], v[112:113] op_sel_hi:[1,0,1]
	v_pk_fma_f32 v[64:65], v[54:55], v[114:115], v[64:65] op_sel_hi:[1,0,1]
	v_add_f32_dpp v66, v66, v66 quad_perm:[1,0,3,2] row_mask:0xf bank_mask:0xf bound_ctrl:1
	v_add_f32_e32 v114, v96, v97
	v_add_f32_dpp v105, v75, v75 row_ror:8 row_mask:0xf bank_mask:0x3 bound_ctrl:1
	v_add_f32_dpp v66, v66, v66 quad_perm:[2,3,0,1] row_mask:0xf bank_mask:0xf bound_ctrl:1
	v_add_f32_dpp v107, v114, v114 row_ror:8 row_mask:0xf bank_mask:0x3 bound_ctrl:1
	ds_read_b128 v[24:27], v72 offset:19968
	ds_read_b128 v[36:39], v72 offset:20224
	v_add_f32_dpp v66, v66, v66 row_half_mirror row_mask:0xf bank_mask:0xf bound_ctrl:1
	ds_read_b128 v[48:51], v72 offset:21632
	ds_read_b128 v[32:35], v72 offset:20736
	v_add_f32_dpp v66, v66, v66 row_mirror row_mask:0xf bank_mask:0xf bound_ctrl:1
	v_pk_fma_f32 v[64:65], v[46:47], v[66:67], v[64:65] op_sel_hi:[1,0,1]
	v_pk_fma_f32 v[112:113], v[44:45], v[66:67], v[112:113] op_sel_hi:[1,0,1]
	s_waitcnt lgkmcnt(11)
	v_pk_mul_f32 v[66:67], v[94:95], v[64:65]
	v_pk_mul_f32 v[58:59], v[58:59], v[64:65]
	v_pk_fma_f32 v[66:67], v[92:93], v[112:113], v[66:67]
	v_pk_mul_f32 v[64:65], v[78:79], v[64:65]
	v_add_f32_e32 v66, v66, v67
	v_pk_fma_f32 v[78:79], v[56:57], v[112:113], v[58:59]
	v_pk_mul_f32 v[76:77], v[76:77], v[112:113]
	v_add_f32_dpp v66, v66, v66 quad_perm:[1,0,3,2] row_mask:0xf bank_mask:0xf bound_ctrl:1
	v_pk_fma_f32 v[64:65], v[98:99], v[82:83], v[64:65] op_sel_hi:[0,1,1]
	v_add_f32_e32 v104, v78, v79
	v_add_f32_dpp v66, v66, v66 quad_perm:[2,3,0,1] row_mask:0xf bank_mask:0xf bound_ctrl:1
	v_pk_fma_f32 v[76:77], v[98:99], v[80:81], v[76:77] op_sel_hi:[0,1,1]
	ds_read_b128 v[40:43], v72 offset:21120
	ds_read_b128 v[52:55], v72 offset:21888
	v_add_f32_dpp v66, v66, v66 row_half_mirror row_mask:0xf bank_mask:0xf bound_ctrl:1
	ds_read_b128 v[44:47], v72 offset:21376
	ds_read_b128 v[56:59], v72 offset:22144
	v_add_f32_dpp v78, v66, v66 row_mirror row_mask:0xf bank_mask:0xf bound_ctrl:1
	v_pk_fma_f32 v[64:65], v[62:63], v[78:79], v[64:65] op_sel_hi:[1,0,1]
	v_pk_fma_f32 v[66:67], v[60:61], v[78:79], v[76:77] op_sel_hi:[1,0,1]
	v_pk_mul_f32 v[102:103], v[86:87], v[64:65]
	v_pk_fma_f32 v[102:103], v[84:85], v[66:67], v[102:103]
	s_waitcnt lgkmcnt(14)
	v_pk_mul_f32 v[2:3], v[64:65], v[2:3]
	v_add_f32_e32 v102, v102, v103
	ds_read_b128 v[60:63], v72 offset:22784
	v_add_f32_dpp v105, v104, v104 row_ror:8 row_mask:0xf bank_mask:0xc bound_ctrl:1
	ds_read_b128 v[76:79], v72 offset:23040
	ds_read_b128 v[80:83], v72 offset:23296
	ds_read_b128 v[84:87], v72 offset:23552
	ds_read_b128 v[112:115], v100 offset:80
	ds_read_b128 v[92:95], v72 offset:22528
	v_add_f32_dpp v107, v102, v102 row_ror:8 row_mask:0xf bank_mask:0xc bound_ctrl:1
	v_pk_fma_f32 v[96:97], v[66:67], v[0:1], v[2:3]
	v_add_f32_dpp v108, v105, v105 row_half_mirror row_mask:0xf bank_mask:0x5 bound_ctrl:1
	v_add_f32_dpp v108, v107, v107 row_half_mirror row_mask:0xf bank_mask:0xa bound_ctrl:1
	ds_read_b128 v[0:3], v72 offset:23936
	v_add_f32_e32 v75, v96, v97
	s_waitcnt lgkmcnt(7)
; template <int CTRL> DI float dppf(float v) { return __int_as_float(__builtin_amdgcn_update_dpp(0, __float_as_int(v), CTRL, 0xf, 0xf, false)); }
; DI float red16(float p) { p += dppf<0xB1>(p); p += dppf<0x4E>(p); p += dppf<0x141>(p); p += dppf<0x140>(p); return p; }
; DI void scan_task(const Params& P, int sb, unsigned char* lds) {
;     ...
;       for (int g4 = 0; g4 < CH / 4; ++g4) {
;         const float* gb = cb + g4 * 4 * SREC;
;         const float4 v4 = *(const float4*)(vrow + g4 * 4);
;         float pp[4];
; #pragma unroll
;         for (int i = 0; i < 4; ++i) {
;           ld_ops(nx3, gb + (i + 3) * SREC, q4);
;           const f2 a01 = {cur.a.x, cur.a.y}, a23 = {cur.a.z, cur.a.w}, w01 = {cur.w.x, cur.w.y}, w23 = {cur.w.z, cur.w.w};
;           const f2 k01 = {cur.k.x, cur.k.y}, k23 = {cur.k.z, cur.k.w}, b01 = {cur.b.x, cur.b.y}, b23 = {cur.b.z, cur.b.w};
;           const f2 r01 = {cur.r.x, cur.r.y}, r23 = {cur.r.z, cur.r.w};
;           f2 pa = S0 * a01; pa += S1 * a23;
;           const float vs = (i == 0) ? v4.x : (i == 1) ? v4.y : (i == 2) ? v4.z : v4.w;
;           const f2 vv = {vs, vs};
;           const f2 t0 = S0 * w01 + vv * k01, t1 = S1 * w23 + vv * k23;
;           const float sa = red16(pa.x + pa.y);
;           const f2 sa2 = {sa, sa};
;           S0 = t0 + sa2 * b01; S1 = t1 + sa2 * b23;
;           f2 py = S0 * r01; py += S1 * r23;
;           pp[i] = py.x + py.y;
;           cur = nxt; nxt = nx2; nx2 = nx3;
;         }
;         const float tA = o1 ? pp[0] : pp[1], kA = o1 ? pp[1] : pp[0];
;         const float tB = o1 ? pp[2] : pp[3], kB = o1 ? pp[3] : pp[2];
;         const float r0 = kA + dppf<0xB1>(tA), r1 = kB + dppf<0xB1>(tB);
;         const float tC = o2 ? r0 : r1, kC = o2 ? r1 : r0;
;         float u = kC + dppf<0x4E>(tC);
;         u += dppf<0x124>(u);
;         u += dppf<0x128>(u);
;         yb[(g4 * 4 + (q & 3)) * 16 + rowl] = u;
	v_add_f32_dpp v108, v108, v108 quad_perm:[1,0,3,2] row_mask:0xf bank_mask:0xf bound_ctrl:1
	v_pk_mul_f32 v[14:15], v[14:15], v[88:89] op_sel_hi:[1,0]
	v_pk_mul_f32 v[12:13], v[12:13], v[88:89] op_sel_hi:[1,0]
	v_add_f32_dpp v108, v108, v108 quad_perm:[2,3,0,1] row_mask:0xf bank_mask:0xf bound_ctrl:1
	v_add_f32_dpp v75, v75, v75 quad_perm:[1,0,3,2] row_mask:0xf bank_mask:0xf bound_ctrl:1
	v_pk_fma_f32 v[64:65], v[64:65], v[10:11], v[14:15]
	v_pk_fma_f32 v[66:67], v[66:67], v[8:9], v[12:13]
	v_add_f32_dpp v75, v75, v75 quad_perm:[2,3,0,1] row_mask:0xf bank_mask:0xf bound_ctrl:1
	v_mov_b32_e32 v98, v91
	ds_write_b32 v73, v108 offset:768
	v_add_f32_dpp v75, v75, v75 row_half_mirror row_mask:0xf bank_mask:0xf bound_ctrl:1
	ds_read_b128 v[8:11], v72 offset:24448
	ds_read_b128 v[12:15], v72 offset:24704
	v_add_f32_dpp v96, v75, v75 row_mirror row_mask:0xf bank_mask:0xf bound_ctrl:1
	v_pk_fma_f32 v[64:65], v[6:7], v[96:97], v[64:65] op_sel_hi:[1,0,1]
	v_pk_fma_f32 v[66:67], v[4:5], v[96:97], v[66:67] op_sel_hi:[1,0,1]
	v_pk_mul_f32 v[18:19], v[18:19], v[64:65]
	v_pk_mul_f32 v[22:23], v[22:23], v[64:65]
	v_pk_mul_f32 v[36:37], v[36:37], v[66:67]
	v_pk_mul_f32 v[38:39], v[38:39], v[64:65]
	v_pk_fma_f32 v[64:65], v[16:17], v[66:67], v[18:19]
	v_pk_fma_f32 v[66:67], v[20:21], v[66:67], v[22:23]
	v_add_f32_e32 v75, v64, v65
	v_add_f32_e32 v64, v66, v67
	v_pk_fma_f32 v[36:37], v[28:29], v[88:89], v[36:37] op_sel:[0,1,0]
	v_pk_fma_f32 v[38:39], v[30:31], v[88:89], v[38:39] op_sel:[0,1,0]
	v_add_f32_dpp v64, v64, v64 quad_perm:[1,0,3,2] row_mask:0xf bank_mask:0xf bound_ctrl:1
	ds_read_b128 v[4:7], v72 offset:24192
	ds_read_b128 v[16:19], v72 offset:24960
	v_add_f32_dpp v64, v64, v64 quad_perm:[2,3,0,1] row_mask:0xf bank_mask:0xf bound_ctrl:1
	ds_read_b128 v[20:23], v72 offset:25344
	ds_read_b128 v[28:31], v72 offset:26112
	v_add_f32_dpp v64, v64, v64 row_half_mirror row_mask:0xf bank_mask:0xf bound_ctrl:1
	s_nop 1
	v_add_f32_dpp v64, v64, v64 row_mirror row_mask:0xf bank_mask:0xf bound_ctrl:1
	v_pk_fma_f32 v[66:67], v[24:25], v[64:65], v[36:37] op_sel_hi:[1,0,1]
	v_pk_fma_f32 v[64:65], v[26:27], v[64:65], v[38:39] op_sel_hi:[1,0,1]
	v_pk_mul_f32 v[88:89], v[48:49], v[66:67]
	v_pk_mul_f32 v[34:35], v[34:35], v[64:65]
	v_pk_mul_f32 v[42:43], v[42:43], v[64:65]
	v_pk_fma_f32 v[96:97], v[32:33], v[66:67], v[34:35]
	v_pk_fma_f32 v[66:67], v[40:41], v[66:67], v[42:43]
	v_pk_mul_f32 v[64:65], v[50:51], v[64:65]
	v_add_f32_e32 v66, v66, v67
	v_pk_fma_f32 v[88:89], v[52:53], v[90:91], v[88:89] op_sel_hi:[1,0,1]
	v_pk_fma_f32 v[64:65], v[54:55], v[90:91], v[64:65] op_sel_hi:[1,0,1]
	v_add_f32_dpp v66, v66, v66 quad_perm:[1,0,3,2] row_mask:0xf bank_mask:0xf bound_ctrl:1
	v_add_f32_e32 v90, v96, v97
	v_add_f32_dpp v105, v75, v75 row_ror:8 row_mask:0xf bank_mask:0x3 bound_ctrl:1
	v_add_f32_dpp v66, v66, v66 quad_perm:[2,3,0,1] row_mask:0xf bank_mask:0xf bound_ctrl:1
	v_add_f32_dpp v107, v90, v90 row_ror:8 row_mask:0xf bank_mask:0x3 bound_ctrl:1
	ds_read_b128 v[24:27], v72 offset:25600
	ds_read_b128 v[36:39], v72 offset:25856
	v_add_f32_dpp v66, v66, v66 row_half_mirror row_mask:0xf bank_mask:0xf bound_ctrl:1
	ds_read_b128 v[48:51], v72 offset:27264
	ds_read_b128 v[32:35], v72 offset:26368
	v_add_f32_dpp v66, v66, v66 row_mirror row_mask:0xf bank_mask:0xf bound_ctrl:1
	v_pk_fma_f32 v[64:65], v[46:47], v[66:67], v[64:65] op_sel_hi:[1,0,1]
	v_pk_fma_f32 v[88:89], v[44:45], v[66:67], v[88:89] op_sel_hi:[1,0,1]
	s_waitcnt lgkmcnt(11)
	v_pk_mul_f32 v[66:67], v[94:95], v[64:65]
	v_pk_mul_f32 v[58:59], v[58:59], v[64:65]
	v_pk_fma_f32 v[66:67], v[92:93], v[88:89], v[66:67]
	v_pk_mul_f32 v[64:65], v[78:79], v[64:65]
	v_add_f32_e32 v66, v66, v67
	v_pk_fma_f32 v[78:79], v[56:57], v[88:89], v[58:59]
	v_pk_mul_f32 v[76:77], v[76:77], v[88:89]
	v_add_f32_dpp v66, v66, v66 quad_perm:[1,0,3,2] row_mask:0xf bank_mask:0xf bound_ctrl:1
	v_pk_fma_f32 v[64:65], v[98:99], v[82:83], v[64:65] op_sel_hi:[0,1,1]
	v_add_f32_e32 v104, v78, v79
	v_add_f32_dpp v66, v66, v66 quad_perm:[2,3,0,1] row_mask:0xf bank_mask:0xf bound_ctrl:1
	v_pk_fma_f32 v[76:77], v[98:99], v[80:81], v[76:77] op_sel_hi:[0,1,1]
	ds_read_b128 v[40:43], v72 offset:26752
	ds_read_b128 v[52:55], v72 offset:27520
	v_add_f32_dpp v66, v66, v66 row_half_mirror row_mask:0xf bank_mask:0xf bound_ctrl:1
	ds_read_b128 v[44:47], v72 offset:27008
	ds_read_b128 v[56:59], v72 offset:27776
	v_add_f32_dpp v78, v66, v66 row_mirror row_mask:0xf bank_mask:0xf bound_ctrl:1
	v_pk_fma_f32 v[64:65], v[62:63], v[78:79], v[64:65] op_sel_hi:[1,0,1]
	v_pk_fma_f32 v[66:67], v[60:61], v[78:79], v[76:77] op_sel_hi:[1,0,1]
	v_pk_mul_f32 v[102:103], v[86:87], v[64:65]
	v_pk_fma_f32 v[102:103], v[84:85], v[66:67], v[102:103]
	s_waitcnt lgkmcnt(14)
	v_pk_mul_f32 v[2:3], v[64:65], v[2:3]
	v_add_f32_e32 v102, v102, v103
	ds_read_b128 v[60:63], v72 offset:28416
	v_add_f32_dpp v105, v104, v104 row_ror:8 row_mask:0xf bank_mask:0xc bound_ctrl:1
	ds_read_b128 v[76:79], v72 offset:28672
	ds_read_b128 v[80:83], v72 offset:28928
	ds_read_b128 v[84:87], v72 offset:29184
	ds_read_b128 v[88:91], v100 offset:96
	ds_read_b128 v[92:95], v72 offset:28160
	v_add_f32_dpp v107, v102, v102 row_ror:8 row_mask:0xf bank_mask:0xc bound_ctrl:1
	v_pk_fma_f32 v[96:97], v[66:67], v[0:1], v[2:3]
	v_add_f32_dpp v108, v105, v105 row_half_mirror row_mask:0xf bank_mask:0x5 bound_ctrl:1
	v_add_f32_dpp v108, v107, v107 row_half_mirror row_mask:0xf bank_mask:0xa bound_ctrl:1
	ds_read_b128 v[0:3], v72 offset:29568
	v_add_f32_e32 v75, v96, v97
	s_waitcnt lgkmcnt(7)
; template <int CTRL> DI float dppf(float v) { return __int_as_float(__builtin_amdgcn_update_dpp(0, __float_as_int(v), CTRL, 0xf, 0xf, false)); }
; DI float red16(float p) { p += dppf<0xB1>(p); p += dppf<0x4E>(p); p += dppf<0x141>(p); p += dppf<0x140>(p); return p; }
; DI void scan_task(const Params& P, int sb, unsigned char* lds) {
;     ...
;       for (int g4 = 0; g4 < CH / 4; ++g4) {
;         const float* gb = cb + g4 * 4 * SREC;
;         const float4 v4 = *(const float4*)(vrow + g4 * 4);
;         float pp[4];
; #pragma unroll
;         for (int i = 0; i < 4; ++i) {
;           ld_ops(nx3, gb + (i + 3) * SREC, q4);
;           const f2 a01 = {cur.a.x, cur.a.y}, a23 = {cur.a.z, cur.a.w}, w01 = {cur.w.x, cur.w.y}, w23 = {cur.w.z, cur.w.w};
;           const f2 k01 = {cur.k.x, cur.k.y}, k23 = {cur.k.z, cur.k.w}, b01 = {cur.b.x, cur.b.y}, b23 = {cur.b.z, cur.b.w};
;           const f2 r01 = {cur.r.x, cur.r.y}, r23 = {cur.r.z, cur.r.w};
;           f2 pa = S0 * a01; pa += S1 * a23;
;           const float vs = (i == 0) ? v4.x : (i == 1) ? v4.y : (i == 2) ? v4.z : v4.w;
;           const f2 vv = {vs, vs};
;           const f2 t0 = S0 * w01 + vv * k01, t1 = S1 * w23 + vv * k23;
;           const float sa = red16(pa.x + pa.y);
;           const f2 sa2 = {sa, sa};
;           S0 = t0 + sa2 * b01; S1 = t1 + sa2 * b23;
;           f2 py = S0 * r01; py += S1 * r23;
;           pp[i] = py.x + py.y;
;           cur = nxt; nxt = nx2; nx2 = nx3;
;         }
;         const float tA = o1 ? pp[0] : pp[1], kA = o1 ? pp[1] : pp[0];
;         const float tB = o1 ? pp[2] : pp[3], kB = o1 ? pp[3] : pp[2];
;         const float r0 = kA + dppf<0xB1>(tA), r1 = kB + dppf<0xB1>(tB);
;         const float tC = o2 ? r0 : r1, kC = o2 ? r1 : r0;
;         float u = kC + dppf<0x4E>(tC);
;         u += dppf<0x124>(u);
;         u += dppf<0x128>(u);
;         yb[(g4 * 4 + (q & 3)) * 16 + rowl] = u;
	v_add_f32_dpp v108, v108, v108 quad_perm:[1,0,3,2] row_mask:0xf bank_mask:0xf bound_ctrl:1
	v_pk_mul_f32 v[14:15], v[14:15], v[112:113] op_sel_hi:[1,0]
	v_pk_mul_f32 v[12:13], v[12:13], v[112:113] op_sel_hi:[1,0]
	v_add_f32_dpp v108, v108, v108 quad_perm:[2,3,0,1] row_mask:0xf bank_mask:0xf bound_ctrl:1
	v_add_f32_dpp v75, v75, v75 quad_perm:[1,0,3,2] row_mask:0xf bank_mask:0xf bound_ctrl:1
	v_pk_fma_f32 v[64:65], v[64:65], v[10:11], v[14:15]
	v_pk_fma_f32 v[66:67], v[66:67], v[8:9], v[12:13]
	v_add_f32_dpp v75, v75, v75 quad_perm:[2,3,0,1] row_mask:0xf bank_mask:0xf bound_ctrl:1
	v_mov_b32_e32 v98, v115
	ds_write_b32 v73, v108 offset:1024
	v_add_f32_dpp v75, v75, v75 row_half_mirror row_mask:0xf bank_mask:0xf bound_ctrl:1
	ds_read_b128 v[8:11], v72 offset:30080
	ds_read_b128 v[12:15], v72 offset:30336
	v_add_f32_dpp v96, v75, v75 row_mirror row_mask:0xf bank_mask:0xf bound_ctrl:1
	v_pk_fma_f32 v[64:65], v[6:7], v[96:97], v[64:65] op_sel_hi:[1,0,1]
	v_pk_fma_f32 v[66:67], v[4:5], v[96:97], v[66:67] op_sel_hi:[1,0,1]
	v_pk_mul_f32 v[18:19], v[18:19], v[64:65]
	v_pk_mul_f32 v[22:23], v[22:23], v[64:65]
	v_pk_mul_f32 v[36:37], v[36:37], v[66:67]
	v_pk_mul_f32 v[38:39], v[38:39], v[64:65]
	v_pk_fma_f32 v[64:65], v[16:17], v[66:67], v[18:19]
	v_pk_fma_f32 v[66:67], v[20:21], v[66:67], v[22:23]
	v_add_f32_e32 v75, v64, v65
	v_add_f32_e32 v64, v66, v67
	v_pk_fma_f32 v[36:37], v[28:29], v[112:113], v[36:37] op_sel:[0,1,0]
	v_pk_fma_f32 v[38:39], v[30:31], v[112:113], v[38:39] op_sel:[0,1,0]
	v_add_f32_dpp v64, v64, v64 quad_perm:[1,0,3,2] row_mask:0xf bank_mask:0xf bound_ctrl:1
	ds_read_b128 v[4:7], v72 offset:29824
	ds_read_b128 v[16:19], v72 offset:30592
	v_add_f32_dpp v64, v64, v64 quad_perm:[2,3,0,1] row_mask:0xf bank_mask:0xf bound_ctrl:1
	ds_read_b128 v[20:23], v72 offset:30976
	ds_read_b128 v[28:31], v72 offset:31744
	v_add_f32_dpp v64, v64, v64 row_half_mirror row_mask:0xf bank_mask:0xf bound_ctrl:1
	s_nop 1
	v_add_f32_dpp v64, v64, v64 row_mirror row_mask:0xf bank_mask:0xf bound_ctrl:1
	v_pk_fma_f32 v[66:67], v[24:25], v[64:65], v[36:37] op_sel_hi:[1,0,1]
	v_pk_fma_f32 v[64:65], v[26:27], v[64:65], v[38:39] op_sel_hi:[1,0,1]
	v_pk_mul_f32 v[112:113], v[48:49], v[66:67]
	v_pk_mul_f32 v[34:35], v[34:35], v[64:65]
	v_pk_mul_f32 v[42:43], v[42:43], v[64:65]
	v_pk_fma_f32 v[96:97], v[32:33], v[66:67], v[34:35]
	v_pk_fma_f32 v[66:67], v[40:41], v[66:67], v[42:43]
	v_pk_mul_f32 v[64:65], v[50:51], v[64:65]
	v_add_f32_e32 v66, v66, v67
	v_pk_fma_f32 v[112:113], v[52:53], v[114:115], v[112:113] op_sel_hi:[1,0,1]
	v_pk_fma_f32 v[64:65], v[54:55], v[114:115], v[64:65] op_sel_hi:[1,0,1]
	v_add_f32_dpp v66, v66, v66 quad_perm:[1,0,3,2] row_mask:0xf bank_mask:0xf bound_ctrl:1
	v_add_f32_e32 v114, v96, v97
	v_add_f32_dpp v105, v75, v75 row_ror:8 row_mask:0xf bank_mask:0x3 bound_ctrl:1
	v_add_f32_dpp v66, v66, v66 quad_perm:[2,3,0,1] row_mask:0xf bank_mask:0xf bound_ctrl:1
	v_add_f32_dpp v107, v114, v114 row_ror:8 row_mask:0xf bank_mask:0x3 bound_ctrl:1
	ds_read_b128 v[24:27], v72 offset:31232
	ds_read_b128 v[36:39], v72 offset:31488
	v_add_f32_dpp v66, v66, v66 row_half_mirror row_mask:0xf bank_mask:0xf bound_ctrl:1
	ds_read_b128 v[48:51], v72 offset:32896
	ds_read_b128 v[32:35], v72 offset:32000
	v_add_f32_dpp v66, v66, v66 row_mirror row_mask:0xf bank_mask:0xf bound_ctrl:1
	v_pk_fma_f32 v[64:65], v[46:47], v[66:67], v[64:65] op_sel_hi:[1,0,1]
	v_pk_fma_f32 v[112:113], v[44:45], v[66:67], v[112:113] op_sel_hi:[1,0,1]
	s_waitcnt lgkmcnt(11)
	v_pk_mul_f32 v[66:67], v[94:95], v[64:65]
	v_pk_mul_f32 v[58:59], v[58:59], v[64:65]
	v_pk_fma_f32 v[66:67], v[92:93], v[112:113], v[66:67]
	v_pk_mul_f32 v[64:65], v[78:79], v[64:65]
	v_add_f32_e32 v66, v66, v67
	v_pk_fma_f32 v[78:79], v[56:57], v[112:113], v[58:59]
	v_pk_mul_f32 v[76:77], v[76:77], v[112:113]
	v_add_f32_dpp v66, v66, v66 quad_perm:[1,0,3,2] row_mask:0xf bank_mask:0xf bound_ctrl:1
	v_pk_fma_f32 v[64:65], v[98:99], v[82:83], v[64:65] op_sel_hi:[0,1,1]
	v_add_f32_e32 v104, v78, v79
	v_add_f32_dpp v66, v66, v66 quad_perm:[2,3,0,1] row_mask:0xf bank_mask:0xf bound_ctrl:1
	v_pk_fma_f32 v[76:77], v[98:99], v[80:81], v[76:77] op_sel_hi:[0,1,1]
	ds_read_b128 v[40:43], v72 offset:32384
	ds_read_b128 v[52:55], v72 offset:33152
	v_add_f32_dpp v66, v66, v66 row_half_mirror row_mask:0xf bank_mask:0xf bound_ctrl:1
	ds_read_b128 v[44:47], v72 offset:32640
	ds_read_b128 v[56:59], v72 offset:33408
	v_add_f32_dpp v78, v66, v66 row_mirror row_mask:0xf bank_mask:0xf bound_ctrl:1
	v_pk_fma_f32 v[64:65], v[62:63], v[78:79], v[64:65] op_sel_hi:[1,0,1]
	v_pk_fma_f32 v[66:67], v[60:61], v[78:79], v[76:77] op_sel_hi:[1,0,1]
	v_pk_mul_f32 v[102:103], v[86:87], v[64:65]
	v_pk_fma_f32 v[102:103], v[84:85], v[66:67], v[102:103]
	s_waitcnt lgkmcnt(14)
	v_pk_mul_f32 v[2:3], v[64:65], v[2:3]
	v_add_f32_e32 v102, v102, v103
	ds_read_b128 v[60:63], v72 offset:34048
	v_add_f32_dpp v105, v104, v104 row_ror:8 row_mask:0xf bank_mask:0xc bound_ctrl:1
	ds_read_b128 v[76:79], v72 offset:34304
	ds_read_b128 v[80:83], v72 offset:34560
	ds_read_b128 v[84:87], v72 offset:34816
	ds_read_b128 v[112:115], v100 offset:112
	ds_read_b128 v[92:95], v72 offset:33792
	v_add_f32_dpp v107, v102, v102 row_ror:8 row_mask:0xf bank_mask:0xc bound_ctrl:1
	v_pk_fma_f32 v[96:97], v[66:67], v[0:1], v[2:3]
	v_add_f32_dpp v108, v105, v105 row_half_mirror row_mask:0xf bank_mask:0x5 bound_ctrl:1
	v_add_f32_dpp v108, v107, v107 row_half_mirror row_mask:0xf bank_mask:0xa bound_ctrl:1
	ds_read_b128 v[0:3], v72 offset:35200
	v_add_f32_e32 v75, v96, v97
	s_waitcnt lgkmcnt(7)
; template <int CTRL> DI float dppf(float v) { return __int_as_float(__builtin_amdgcn_update_dpp(0, __float_as_int(v), CTRL, 0xf, 0xf, false)); }
; DI float red16(float p) { p += dppf<0xB1>(p); p += dppf<0x4E>(p); p += dppf<0x141>(p); p += dppf<0x140>(p); return p; }
; DI void scan_task(const Params& P, int sb, unsigned char* lds) {
;     ...
;       for (int g4 = 0; g4 < CH / 4; ++g4) {
;         const float* gb = cb + g4 * 4 * SREC;
;         const float4 v4 = *(const float4*)(vrow + g4 * 4);
;         float pp[4];
; #pragma unroll
;         for (int i = 0; i < 4; ++i) {
;           ld_ops(nx3, gb + (i + 3) * SREC, q4);
;           const f2 a01 = {cur.a.x, cur.a.y}, a23 = {cur.a.z, cur.a.w}, w01 = {cur.w.x, cur.w.y}, w23 = {cur.w.z, cur.w.w};
;           const f2 k01 = {cur.k.x, cur.k.y}, k23 = {cur.k.z, cur.k.w}, b01 = {cur.b.x, cur.b.y}, b23 = {cur.b.z, cur.b.w};
;           const f2 r01 = {cur.r.x, cur.r.y}, r23 = {cur.r.z, cur.r.w};
;           f2 pa = S0 * a01; pa += S1 * a23;
;           const float vs = (i == 0) ? v4.x : (i == 1) ? v4.y : (i == 2) ? v4.z : v4.w;
;           const f2 vv = {vs, vs};
;           const f2 t0 = S0 * w01 + vv * k01, t1 = S1 * w23 + vv * k23;
;           const float sa = red16(pa.x + pa.y);
;           const f2 sa2 = {sa, sa};
;           S0 = t0 + sa2 * b01; S1 = t1 + sa2 * b23;
;           f2 py = S0 * r01; py += S1 * r23;
;           pp[i] = py.x + py.y;
;           cur = nxt; nxt = nx2; nx2 = nx3;
;         }
;         const float tA = o1 ? pp[0] : pp[1], kA = o1 ? pp[1] : pp[0];
;         const float tB = o1 ? pp[2] : pp[3], kB = o1 ? pp[3] : pp[2];
;         const float r0 = kA + dppf<0xB1>(tA), r1 = kB + dppf<0xB1>(tB);
;         const float tC = o2 ? r0 : r1, kC = o2 ? r1 : r0;
;         float u = kC + dppf<0x4E>(tC);
;         u += dppf<0x124>(u);
;         u += dppf<0x128>(u);
;         yb[(g4 * 4 + (q & 3)) * 16 + rowl] = u;
	v_add_f32_dpp v108, v108, v108 quad_perm:[1,0,3,2] row_mask:0xf bank_mask:0xf bound_ctrl:1
	v_pk_mul_f32 v[14:15], v[14:15], v[88:89] op_sel_hi:[1,0]
	v_pk_mul_f32 v[12:13], v[12:13], v[88:89] op_sel_hi:[1,0]
	v_add_f32_dpp v108, v108, v108 quad_perm:[2,3,0,1] row_mask:0xf bank_mask:0xf bound_ctrl:1
	v_add_f32_dpp v75, v75, v75 quad_perm:[1,0,3,2] row_mask:0xf bank_mask:0xf bound_ctrl:1
	v_pk_fma_f32 v[64:65], v[64:65], v[10:11], v[14:15]
	v_pk_fma_f32 v[66:67], v[66:67], v[8:9], v[12:13]
	v_add_f32_dpp v75, v75, v75 quad_perm:[2,3,0,1] row_mask:0xf bank_mask:0xf bound_ctrl:1
	v_mov_b32_e32 v98, v91
	ds_write_b32 v73, v108 offset:1280
	v_add_f32_dpp v75, v75, v75 row_half_mirror row_mask:0xf bank_mask:0xf bound_ctrl:1
	ds_read_b128 v[8:11], v72 offset:35712
	ds_read_b128 v[12:15], v72 offset:35968
	v_add_f32_dpp v96, v75, v75 row_mirror row_mask:0xf bank_mask:0xf bound_ctrl:1
	v_pk_fma_f32 v[64:65], v[6:7], v[96:97], v[64:65] op_sel_hi:[1,0,1]
	v_pk_fma_f32 v[66:67], v[4:5], v[96:97], v[66:67] op_sel_hi:[1,0,1]
	v_pk_mul_f32 v[18:19], v[18:19], v[64:65]
	v_pk_mul_f32 v[22:23], v[22:23], v[64:65]
	v_pk_mul_f32 v[36:37], v[36:37], v[66:67]
	v_pk_mul_f32 v[38:39], v[38:39], v[64:65]
	v_pk_fma_f32 v[64:65], v[16:17], v[66:67], v[18:19]
	v_pk_fma_f32 v[66:67], v[20:21], v[66:67], v[22:23]
	v_add_f32_e32 v75, v64, v65
	v_add_f32_e32 v64, v66, v67
	v_pk_fma_f32 v[36:37], v[28:29], v[88:89], v[36:37] op_sel:[0,1,0]
	v_pk_fma_f32 v[38:39], v[30:31], v[88:89], v[38:39] op_sel:[0,1,0]
	v_add_f32_dpp v64, v64, v64 quad_perm:[1,0,3,2] row_mask:0xf bank_mask:0xf bound_ctrl:1
	ds_read_b128 v[4:7], v72 offset:35456
	ds_read_b128 v[16:19], v72 offset:36224
	v_add_f32_dpp v64, v64, v64 quad_perm:[2,3,0,1] row_mask:0xf bank_mask:0xf bound_ctrl:1
	ds_read_b128 v[20:23], v72 offset:36608
	ds_read_b128 v[28:31], v72 offset:37376
	v_add_f32_dpp v64, v64, v64 row_half_mirror row_mask:0xf bank_mask:0xf bound_ctrl:1
	s_nop 1
	v_add_f32_dpp v64, v64, v64 row_mirror row_mask:0xf bank_mask:0xf bound_ctrl:1
	v_pk_fma_f32 v[66:67], v[24:25], v[64:65], v[36:37] op_sel_hi:[1,0,1]
	v_pk_fma_f32 v[64:65], v[26:27], v[64:65], v[38:39] op_sel_hi:[1,0,1]
	v_pk_mul_f32 v[88:89], v[48:49], v[66:67]
	v_pk_mul_f32 v[34:35], v[34:35], v[64:65]
	v_pk_mul_f32 v[42:43], v[42:43], v[64:65]
	v_pk_fma_f32 v[96:97], v[32:33], v[66:67], v[34:35]
	v_pk_fma_f32 v[66:67], v[40:41], v[66:67], v[42:43]
	v_pk_mul_f32 v[64:65], v[50:51], v[64:65]
	v_add_f32_e32 v66, v66, v67
	v_pk_fma_f32 v[88:89], v[52:53], v[90:91], v[88:89] op_sel_hi:[1,0,1]
	v_pk_fma_f32 v[64:65], v[54:55], v[90:91], v[64:65] op_sel_hi:[1,0,1]
	v_add_f32_dpp v66, v66, v66 quad_perm:[1,0,3,2] row_mask:0xf bank_mask:0xf bound_ctrl:1
	v_add_f32_e32 v90, v96, v97
	v_add_f32_dpp v105, v75, v75 row_ror:8 row_mask:0xf bank_mask:0x3 bound_ctrl:1
	v_add_f32_dpp v66, v66, v66 quad_perm:[2,3,0,1] row_mask:0xf bank_mask:0xf bound_ctrl:1
	v_add_f32_dpp v107, v90, v90 row_ror:8 row_mask:0xf bank_mask:0x3 bound_ctrl:1
	ds_read_b128 v[24:27], v72 offset:36864
	ds_read_b128 v[36:39], v72 offset:37120
	v_add_f32_dpp v66, v66, v66 row_half_mirror row_mask:0xf bank_mask:0xf bound_ctrl:1
	ds_read_b128 v[48:51], v72 offset:38528
	ds_read_b128 v[32:35], v72 offset:37632
	v_add_f32_dpp v66, v66, v66 row_mirror row_mask:0xf bank_mask:0xf bound_ctrl:1
	v_pk_fma_f32 v[64:65], v[46:47], v[66:67], v[64:65] op_sel_hi:[1,0,1]
	v_pk_fma_f32 v[88:89], v[44:45], v[66:67], v[88:89] op_sel_hi:[1,0,1]
	s_waitcnt lgkmcnt(11)
	v_pk_mul_f32 v[66:67], v[94:95], v[64:65]
	v_pk_mul_f32 v[58:59], v[58:59], v[64:65]
	v_pk_fma_f32 v[66:67], v[92:93], v[88:89], v[66:67]
	v_pk_mul_f32 v[64:65], v[78:79], v[64:65]
	v_add_f32_e32 v66, v66, v67
	v_pk_fma_f32 v[78:79], v[56:57], v[88:89], v[58:59]
	v_pk_mul_f32 v[76:77], v[76:77], v[88:89]
	v_add_f32_dpp v66, v66, v66 quad_perm:[1,0,3,2] row_mask:0xf bank_mask:0xf bound_ctrl:1
	v_pk_fma_f32 v[64:65], v[98:99], v[82:83], v[64:65] op_sel_hi:[0,1,1]
	v_add_f32_e32 v104, v78, v79
	v_add_f32_dpp v66, v66, v66 quad_perm:[2,3,0,1] row_mask:0xf bank_mask:0xf bound_ctrl:1
	v_pk_fma_f32 v[76:77], v[98:99], v[80:81], v[76:77] op_sel_hi:[0,1,1]
	ds_read_b128 v[40:43], v72 offset:38016
	ds_read_b128 v[52:55], v72 offset:38784
	v_add_f32_dpp v66, v66, v66 row_half_mirror row_mask:0xf bank_mask:0xf bound_ctrl:1
	ds_read_b128 v[44:47], v72 offset:38272
	ds_read_b128 v[56:59], v72 offset:39040
	v_add_f32_dpp v78, v66, v66 row_mirror row_mask:0xf bank_mask:0xf bound_ctrl:1
	v_pk_fma_f32 v[64:65], v[62:63], v[78:79], v[64:65] op_sel_hi:[1,0,1]
	v_pk_fma_f32 v[66:67], v[60:61], v[78:79], v[76:77] op_sel_hi:[1,0,1]
	v_pk_mul_f32 v[102:103], v[86:87], v[64:65]
	v_pk_fma_f32 v[102:103], v[84:85], v[66:67], v[102:103]
	s_waitcnt lgkmcnt(14)
	v_pk_mul_f32 v[2:3], v[64:65], v[2:3]
	v_add_f32_e32 v102, v102, v103
	ds_read_b128 v[60:63], v72 offset:39680
	v_add_f32_dpp v105, v104, v104 row_ror:8 row_mask:0xf bank_mask:0xc bound_ctrl:1
	ds_read_b128 v[76:79], v72 offset:39936
	ds_read_b128 v[80:83], v72 offset:40192
	ds_read_b128 v[84:87], v72 offset:40448
	ds_read_b128 v[92:95], v72 offset:39424
	v_add_f32_dpp v107, v102, v102 row_ror:8 row_mask:0xf bank_mask:0xc bound_ctrl:1
	v_pk_fma_f32 v[96:97], v[66:67], v[0:1], v[2:3]
	v_add_f32_dpp v108, v105, v105 row_half_mirror row_mask:0xf bank_mask:0x5 bound_ctrl:1
	v_add_f32_dpp v108, v107, v107 row_half_mirror row_mask:0xf bank_mask:0xa bound_ctrl:1
	ds_read_b128 v[0:3], v72 offset:40832
	v_add_f32_e32 v75, v96, v97
	s_waitcnt lgkmcnt(6)
; template <int CTRL> DI float dppf(float v) { return __int_as_float(__builtin_amdgcn_update_dpp(0, __float_as_int(v), CTRL, 0xf, 0xf, false)); }
; DI float red16(float p) { p += dppf<0xB1>(p); p += dppf<0x4E>(p); p += dppf<0x141>(p); p += dppf<0x140>(p); return p; }
; DI void scan_task(const Params& P, int sb, unsigned char* lds) {
;     ...
;       for (int g4 = 0; g4 < CH / 4; ++g4) {
;         const float* gb = cb + g4 * 4 * SREC;
;         const float4 v4 = *(const float4*)(vrow + g4 * 4);
;         float pp[4];
; #pragma unroll
;         for (int i = 0; i < 4; ++i) {
;           ld_ops(nx3, gb + (i + 3) * SREC, q4);
;           const f2 a01 = {cur.a.x, cur.a.y}, a23 = {cur.a.z, cur.a.w}, w01 = {cur.w.x, cur.w.y}, w23 = {cur.w.z, cur.w.w};
;           const f2 k01 = {cur.k.x, cur.k.y}, k23 = {cur.k.z, cur.k.w}, b01 = {cur.b.x, cur.b.y}, b23 = {cur.b.z, cur.b.w};
;           const f2 r01 = {cur.r.x, cur.r.y}, r23 = {cur.r.z, cur.r.w};
;           f2 pa = S0 * a01; pa += S1 * a23;
;           const float vs = (i == 0) ? v4.x : (i == 1) ? v4.y : (i == 2) ? v4.z : v4.w;
;           const f2 vv = {vs, vs};
;           const f2 t0 = S0 * w01 + vv * k01, t1 = S1 * w23 + vv * k23;
;           const float sa = red16(pa.x + pa.y);
;           const f2 sa2 = {sa, sa};
;           S0 = t0 + sa2 * b01; S1 = t1 + sa2 * b23;
;           f2 py = S0 * r01; py += S1 * r23;
;           pp[i] = py.x + py.y;
;           cur = nxt; nxt = nx2; nx2 = nx3;
;         }
;         const float tA = o1 ? pp[0] : pp[1], kA = o1 ? pp[1] : pp[0];
;         const float tB = o1 ? pp[2] : pp[3], kB = o1 ? pp[3] : pp[2];
;         const float r0 = kA + dppf<0xB1>(tA), r1 = kB + dppf<0xB1>(tB);
;         const float tC = o2 ? r0 : r1, kC = o2 ? r1 : r0;
;         float u = kC + dppf<0x4E>(tC);
;         u += dppf<0x124>(u);
;         u += dppf<0x128>(u);
;         yb[(g4 * 4 + (q & 3)) * 16 + rowl] = u;
;       }
;       __syncthreads();
	v_add_f32_dpp v108, v108, v108 quad_perm:[1,0,3,2] row_mask:0xf bank_mask:0xf bound_ctrl:1
	v_pk_mul_f32 v[14:15], v[14:15], v[112:113] op_sel_hi:[1,0]
	v_pk_mul_f32 v[12:13], v[12:13], v[112:113] op_sel_hi:[1,0]
	v_add_f32_dpp v108, v108, v108 quad_perm:[2,3,0,1] row_mask:0xf bank_mask:0xf bound_ctrl:1
	v_add_f32_dpp v75, v75, v75 quad_perm:[1,0,3,2] row_mask:0xf bank_mask:0xf bound_ctrl:1
	v_pk_fma_f32 v[64:65], v[64:65], v[10:11], v[14:15]
	v_pk_fma_f32 v[66:67], v[66:67], v[8:9], v[12:13]
	v_add_f32_dpp v75, v75, v75 quad_perm:[2,3,0,1] row_mask:0xf bank_mask:0xf bound_ctrl:1
	v_mov_b32_e32 v98, v115
	ds_write_b32 v73, v108 offset:1536
	v_add_f32_dpp v75, v75, v75 row_half_mirror row_mask:0xf bank_mask:0xf bound_ctrl:1
	ds_read_b128 v[8:11], v72 offset:41344
	ds_read_b128 v[12:15], v72 offset:41600
	v_add_f32_dpp v96, v75, v75 row_mirror row_mask:0xf bank_mask:0xf bound_ctrl:1
	v_pk_fma_f32 v[64:65], v[6:7], v[96:97], v[64:65] op_sel_hi:[1,0,1]
	v_pk_fma_f32 v[66:67], v[4:5], v[96:97], v[66:67] op_sel_hi:[1,0,1]
	v_pk_mul_f32 v[18:19], v[18:19], v[64:65]
	v_pk_mul_f32 v[22:23], v[22:23], v[64:65]
	v_pk_mul_f32 v[36:37], v[36:37], v[66:67]
	v_pk_mul_f32 v[38:39], v[38:39], v[64:65]
	v_pk_fma_f32 v[64:65], v[16:17], v[66:67], v[18:19]
	v_pk_fma_f32 v[66:67], v[20:21], v[66:67], v[22:23]
	v_add_f32_e32 v75, v64, v65
	v_add_f32_e32 v64, v66, v67
	v_pk_fma_f32 v[36:37], v[28:29], v[112:113], v[36:37] op_sel:[0,1,0]
	v_pk_fma_f32 v[38:39], v[30:31], v[112:113], v[38:39] op_sel:[0,1,0]
	v_add_f32_dpp v64, v64, v64 quad_perm:[1,0,3,2] row_mask:0xf bank_mask:0xf bound_ctrl:1
	ds_read_b128 v[4:7], v72 offset:41088
	ds_read_b128 v[16:19], v72 offset:41856
	v_add_f32_dpp v64, v64, v64 quad_perm:[2,3,0,1] row_mask:0xf bank_mask:0xf bound_ctrl:1
	ds_read_b128 v[20:23], v72 offset:42240
	ds_read_b128 v[28:31], v72 offset:43008
	v_add_f32_dpp v64, v64, v64 row_half_mirror row_mask:0xf bank_mask:0xf bound_ctrl:1
	s_nop 1
	v_add_f32_dpp v64, v64, v64 row_mirror row_mask:0xf bank_mask:0xf bound_ctrl:1
	v_pk_fma_f32 v[66:67], v[24:25], v[64:65], v[36:37] op_sel_hi:[1,0,1]
	v_pk_fma_f32 v[64:65], v[26:27], v[64:65], v[38:39] op_sel_hi:[1,0,1]
	v_pk_mul_f32 v[112:113], v[48:49], v[66:67]
	v_pk_mul_f32 v[34:35], v[34:35], v[64:65]
	v_pk_mul_f32 v[42:43], v[42:43], v[64:65]
	v_pk_fma_f32 v[96:97], v[32:33], v[66:67], v[34:35]
	v_pk_fma_f32 v[66:67], v[40:41], v[66:67], v[42:43]
	v_pk_mul_f32 v[64:65], v[50:51], v[64:65]
	v_add_f32_e32 v66, v66, v67
	v_pk_fma_f32 v[112:113], v[52:53], v[114:115], v[112:113] op_sel_hi:[1,0,1]
	v_pk_fma_f32 v[64:65], v[54:55], v[114:115], v[64:65] op_sel_hi:[1,0,1]
	v_add_f32_dpp v66, v66, v66 quad_perm:[1,0,3,2] row_mask:0xf bank_mask:0xf bound_ctrl:1
	v_add_f32_e32 v114, v96, v97
	v_add_f32_dpp v105, v75, v75 row_ror:8 row_mask:0xf bank_mask:0x3 bound_ctrl:1
	v_add_f32_dpp v66, v66, v66 quad_perm:[2,3,0,1] row_mask:0xf bank_mask:0xf bound_ctrl:1
	v_add_f32_dpp v107, v114, v114 row_ror:8 row_mask:0xf bank_mask:0x3 bound_ctrl:1
	ds_read_b128 v[24:27], v72 offset:42496
	ds_read_b128 v[36:39], v72 offset:42752
	v_add_f32_dpp v66, v66, v66 row_half_mirror row_mask:0xf bank_mask:0xf bound_ctrl:1
	ds_read_b128 v[48:51], v72 offset:44160
	ds_read_b128 v[32:35], v72 offset:43264
	v_add_f32_dpp v66, v66, v66 row_mirror row_mask:0xf bank_mask:0xf bound_ctrl:1
	v_pk_fma_f32 v[64:65], v[46:47], v[66:67], v[64:65] op_sel_hi:[1,0,1]
	v_pk_fma_f32 v[112:113], v[44:45], v[66:67], v[112:113] op_sel_hi:[1,0,1]
	s_waitcnt lgkmcnt(11)
	v_pk_mul_f32 v[66:67], v[94:95], v[64:65]
	v_pk_mul_f32 v[58:59], v[58:59], v[64:65]
	v_pk_fma_f32 v[66:67], v[92:93], v[112:113], v[66:67]
	v_pk_mul_f32 v[64:65], v[78:79], v[64:65]
	v_add_f32_e32 v66, v66, v67
	v_pk_fma_f32 v[78:79], v[56:57], v[112:113], v[58:59]
	v_pk_mul_f32 v[76:77], v[76:77], v[112:113]
	v_add_f32_dpp v66, v66, v66 quad_perm:[1,0,3,2] row_mask:0xf bank_mask:0xf bound_ctrl:1
	v_pk_fma_f32 v[64:65], v[98:99], v[82:83], v[64:65] op_sel_hi:[0,1,1]
	v_add_f32_e32 v104, v78, v79
	v_add_f32_dpp v66, v66, v66 quad_perm:[2,3,0,1] row_mask:0xf bank_mask:0xf bound_ctrl:1
	v_pk_fma_f32 v[76:77], v[98:99], v[80:81], v[76:77] op_sel_hi:[0,1,1]
	ds_read_b128 v[40:43], v72 offset:43648
	ds_read_b128 v[52:55], v72 offset:44416
	v_add_f32_dpp v66, v66, v66 row_half_mirror row_mask:0xf bank_mask:0xf bound_ctrl:1
	ds_read_b128 v[44:47], v72 offset:43904
	ds_read_b128 v[56:59], v72 offset:44672
	v_add_f32_dpp v78, v66, v66 row_mirror row_mask:0xf bank_mask:0xf bound_ctrl:1
	v_pk_fma_f32 v[64:65], v[62:63], v[78:79], v[64:65] op_sel_hi:[1,0,1]
	v_pk_fma_f32 v[66:67], v[60:61], v[78:79], v[76:77] op_sel_hi:[1,0,1]
	v_pk_mul_f32 v[102:103], v[86:87], v[64:65]
	v_pk_fma_f32 v[102:103], v[84:85], v[66:67], v[102:103]
	s_nop 0
	v_add_f32_e32 v102, v102, v103
	v_add_f32_dpp v105, v104, v104 row_ror:8 row_mask:0xf bank_mask:0xc bound_ctrl:1
	s_nop 1
	v_add_f32_dpp v107, v102, v102 row_ror:8 row_mask:0xf bank_mask:0xc bound_ctrl:1
	v_add_f32_dpp v108, v105, v105 row_half_mirror row_mask:0xf bank_mask:0x5 bound_ctrl:1
	s_nop 1
	v_add_f32_dpp v108, v107, v107 row_half_mirror row_mask:0xf bank_mask:0xa bound_ctrl:1
	s_nop 1
	v_add_f32_dpp v108, v108, v108 quad_perm:[1,0,3,2] row_mask:0xf bank_mask:0xf bound_ctrl:1
	s_nop 1
	v_add_f32_dpp v108, v108, v108 quad_perm:[2,3,0,1] row_mask:0xf bank_mask:0xf bound_ctrl:1
	ds_write_b32 v73, v108 offset:1792
	s_add_i32 s0, s0, 1
	s_xor_b64 s[6:7], s[6:7], -1
	s_cmpk_eq_i32 s0, 0x108
	s_waitcnt lgkmcnt(0)
	s_barrier
	s_cbranch_scc0 .LBB0_1197
	s_setprio 0
	s_mov_b64 s[4:5], 0

;     ...
;   for (;;) {
;     __syncthreads();
;     if (threadIdx.x == 0) *sh_item = atomicAdd(ctr, 1);
;     __syncthreads();
;     const int item = *sh_item;
;     if (item >= 256) break;
;     attn_item(P, item, lds);
.LBB0_1235:
	v_readfirstlane_b32 s6, v208
	s_cmpk_lt_u32 s6, 0x100
	s_cbranch_scc1 .Lattn_prio_skip
	s_setprio 1

; DI unsigned xb_ld(unsigned* p) { return __hip_atomic_load(p, __ATOMIC_RELAXED, __HIP_MEMORY_SCOPE_AGENT); }
; DI void xcd_barrier_complete(unsigned* bar, unsigned x, unsigned& nloc, unsigned& nx) {
;   const unsigned G = gridDim.x;
;   unsigned sum, cnt, mine, sp = 0u;
;   for (;;) {
;     sum = 0u; cnt = 0u; mine = 0u;
; #pragma unroll
;     for (unsigned j = 0; j < 16; ++j) { const unsigned c = xb_ld(&bar[XB_XCNT(j)]); sum += c; cnt += (c > 0u) ? 1u : 0u; mine = (j == x) ? c : mine; }
; DI void xcd_barrier(const XcdBarrier& b) {
;   asm volatile("s_waitcnt vmcnt(0)" ::: "memory");
;   __syncthreads();
;   if (threadIdx.x == 0) {
;     unsigned* bar = b.bar;
;     __builtin_amdgcn_s_waitcnt(0);
;     unsigned nloc = b.st[0], nx = b.st[1];
;     if (nloc == 0u) { xcd_barrier_complete(bar, b.x, nloc, nx); b.st[0] = nloc; b.st[1] = nx; }
.LBB0_1267:
	s_setprio 0
	s_cmp_lt_i32 s97, 7
	s_cbranch_scc1 .LBB0_1321
	s_waitcnt vmcnt(0)
	s_barrier
	s_and_saveexec_b64 s[4:5], s[42:43]
	s_cbranch_execz .LBB0_1320
	s_mov_b64 s[0:1], src_shared_base
	v_mov_b32_e32 v0, 0x24100
	v_mov_b32_e32 v1, s1
	s_waitcnt vmcnt(0) expcnt(0) lgkmcnt(0)
	flat_load_dword v2, v[0:1] sc0 sc1
	s_waitcnt vmcnt(0)
	v_mov_b32_e32 v0, 0x24104
	flat_load_dword v0, v[0:1] sc0 sc1
	s_waitcnt vmcnt(0) lgkmcnt(0)
	v_cmp_eq_u32_e32 vcc, 0, v2
	s_and_saveexec_b64 s[6:7], vcc
	s_cbranch_execz .LBB0_1284
	s_add_u32 s8, s94, 0xa200
	s_addc_u32 s9, s95, 0
	s_add_u32 s10, s94, 0xa400
	s_addc_u32 s11, s95, 0
	s_add_u32 s12, s94, 0xa500
	s_addc_u32 s13, s95, 0
	s_add_u32 s14, s94, 0xa600
	s_addc_u32 s15, s95, 0
	s_add_u32 s16, s94, 0xa700
	s_addc_u32 s17, s95, 0
	s_add_u32 s18, s94, 0xa800
	s_addc_u32 s19, s95, 0
	s_add_u32 s20, s94, 0xa900
	s_addc_u32 s21, s95, 0
	s_add_u32 s22, s94, 0xaa00
	s_addc_u32 s23, s95, 0
	s_add_u32 s24, s94, 0xab00
	s_addc_u32 s25, s95, 0
	s_add_u32 s26, s94, 0xac00
	s_addc_u32 s27, s95, 0
	s_add_u32 s28, s94, 0xad00
	s_addc_u32 s29, s95, 0
	s_add_u32 s30, s94, 0xae00
	s_addc_u32 s31, s95, 0
	s_add_u32 s34, s94, 0xaf00
	s_addc_u32 s35, s95, 0
	s_add_u32 s36, s94, 0xb000
	s_addc_u32 s37, s95, 0
	s_add_u32 s38, s94, 0xb100
	s_addc_u32 s39, s95, 0
	s_add_u32 s40, s94, 0xb200
	s_addc_u32 s41, s95, 0
	s_add_u32 s48, s94, 0xb300
	s_addc_u32 s49, s95, 0
	s_mov_b32 s0, 1
	v_mov_b32_e32 v16, 0
	s_branch .LBB0_1272
